# up-proj skinny: hand pipeline (2 stages of 2 chunks in flight) + nt on its A and W loads
# speedup vs baseline: 1.0032x; 1.0032x over previous
; #define SK_LOAD(buf, c) do { _Pragma("unroll") for (int nt = 0; nt < 2; ++nt) fb[buf][nt] = *(const bf16x8*)(pb + nt * rs + 32 * (c)); \
;         _Pragma("unroll") for (int mt = 0; mt < NMT; ++mt) fa[buf][mt] = *(const bf16x8*)(pa + mt * rs + 32 * (c)); } while (0)
; #define SK_MMA(buf) do { _Pragma("unroll") for (int mt = 0; mt < NMT; ++mt) _Pragma("unroll") for (int nt = 0; nt < 2; ++nt) \
;         acc[mt][nt] = __builtin_amdgcn_mfma_f32_16x16x32_bf16(fa[buf][mt], fb[buf][nt], acc[mt][nt], 0, 0, 0); } while (0)
; template <int MT, class Epi>
; DI void skinny_unit(LAS unsigned char* lds, const bf16_t* A, const bf16_t* Wt, int K, int cgi, int k0, int row0, const Epi& E, int tid) {
;     ...
;     const bf16_t* pa = A + (size_t)(row0 + fr) * K + k0 + wid * 256 + 8 * fq;
;     const bf16_t* pb = Wt + (size_t)(c0 + fr) * K + k0 + wid * 256 + 8 * fq;
;     const size_t rs = (size_t)16 * K;
;     f32x4 acc[NMT][2];
; #pragma unroll
;     for (int i = 0; i < NMT; ++i) { acc[i][0] = (f32x4){0.f, 0.f, 0.f, 0.f}; acc[i][1] = (f32x4){0.f, 0.f, 0.f, 0.f}; }
;     bf16x8 fb[3][2], fa[3][NMT];
;     ...
;     SK_LOAD(0, 0); SK_LOAD(1, 1);
;     SK_LOAD(2, 2); SK_MMA(0);
;     SK_LOAD(0, 3); SK_MMA(1);
;     SK_LOAD(1, 4); SK_MMA(2);
;     SK_LOAD(2, 5); SK_MMA(0);
;     SK_LOAD(0, 6); SK_MMA(1);
;     SK_LOAD(1, 7); SK_MMA(2);
;     SK_MMA(0); SK_MMA(1);
; __global__ void __launch_bounds__(512, 2) fwd_kernel(Args a) {
;     ...
;         for (int u = bx; u < FF / 32; u += G) skinny_unit<4>(lds, XG + (size_t)LP * DM, WUP, DM, u, 0, 0, SE, tid);
.Lsk6_loop:
	s_add_u32 s8, s2, 0x0
	s_addc_u32 s9, s3, 0
	s_add_u32 s10, s2, 0x10000
	s_addc_u32 s11, s3, 0
	s_add_u32 s12, s2, 0x20000
	s_addc_u32 s13, s3, 0
	s_add_u32 s14, s2, 0x30000
	s_addc_u32 s15, s3, 0
	s_add_u32 s24, s2, 0x40000
	s_addc_u32 s25, s3, 0
	s_add_u32 s26, s2, 0x50000
	s_addc_u32 s27, s3, 0
	s_add_u32 s28, s2, 0x60000
	s_addc_u32 s29, s3, 0
	s_add_u32 s30, s2, 0x70000
	s_addc_u32 s31, s3, 0
	s_lshl_b32 s34, s0, 17
	s_add_u32 s34, s6, s34
	s_addc_u32 s35, s7, 0
	s_add_u32 s36, s34, 0x10000
	s_addc_u32 s37, s35, 0
	s_lshl_b32 s38, s0, 6
	s_add_u32 s38, s38, 0x12400000
	s_add_u32 s38, s60, s38
	s_addc_u32 s39, s61, 0
	global_load_dwordx4 v[108:111], v64, s[34:35] offset:0 nt
	global_load_dwordx4 v[148:151], v64, s[34:35] offset:64 nt
	global_load_dwordx4 v[112:115], v64, s[36:37] offset:0 nt
	global_load_dwordx4 v[152:155], v64, s[36:37] offset:64 nt
	global_load_dwordx4 v[76:79], v64, s[8:9] offset:0 nt
	global_load_dwordx4 v[116:119], v64, s[8:9] offset:64 nt
	global_load_dwordx4 v[80:83], v64, s[10:11] offset:0 nt
	global_load_dwordx4 v[120:123], v64, s[10:11] offset:64 nt
	global_load_dwordx4 v[84:87], v64, s[12:13] offset:0 nt
	global_load_dwordx4 v[124:127], v64, s[12:13] offset:64 nt
	global_load_dwordx4 v[88:91], v64, s[14:15] offset:0 nt
	global_load_dwordx4 v[128:131], v64, s[14:15] offset:64 nt
	global_load_dwordx4 v[92:95], v64, s[24:25] offset:0 nt
	global_load_dwordx4 v[132:135], v64, s[24:25] offset:64 nt
	global_load_dwordx4 v[96:99], v64, s[26:27] offset:0 nt
	global_load_dwordx4 v[136:139], v64, s[26:27] offset:64 nt
	global_load_dwordx4 v[100:103], v64, s[28:29] offset:0 nt
	global_load_dwordx4 v[140:143], v64, s[28:29] offset:64 nt
	global_load_dwordx4 v[104:107], v64, s[30:31] offset:0 nt
	global_load_dwordx4 v[144:147], v64, s[30:31] offset:64 nt
	global_load_dwordx4 v[188:191], v64, s[34:35] offset:128 nt
	global_load_dwordx4 v[228:231], v64, s[34:35] offset:192 nt
	global_load_dwordx4 v[192:195], v64, s[36:37] offset:128 nt
	global_load_dwordx4 v[232:235], v64, s[36:37] offset:192 nt
	global_load_dwordx4 v[156:159], v64, s[8:9] offset:128 nt
	global_load_dwordx4 v[196:199], v64, s[8:9] offset:192 nt
	global_load_dwordx4 v[160:163], v64, s[10:11] offset:128 nt
	global_load_dwordx4 v[200:203], v64, s[10:11] offset:192 nt
	global_load_dwordx4 v[164:167], v64, s[12:13] offset:128 nt
	global_load_dwordx4 v[204:207], v64, s[12:13] offset:192 nt
	global_load_dwordx4 v[168:171], v64, s[14:15] offset:128 nt
	global_load_dwordx4 v[208:211], v64, s[14:15] offset:192 nt
	global_load_dwordx4 v[172:175], v64, s[24:25] offset:128 nt
	global_load_dwordx4 v[212:215], v64, s[24:25] offset:192 nt
	global_load_dwordx4 v[176:179], v64, s[26:27] offset:128 nt
	global_load_dwordx4 v[216:219], v64, s[26:27] offset:192 nt
	global_load_dwordx4 v[180:183], v64, s[28:29] offset:128 nt
	global_load_dwordx4 v[220:223], v64, s[28:29] offset:192 nt
	global_load_dwordx4 v[184:187], v64, s[30:31] offset:128 nt
	global_load_dwordx4 v[224:227], v64, s[30:31] offset:192 nt
	s_waitcnt vmcnt(20)
	v_mfma_f32_16x16x32_bf16 v[0:3], v[76:79], v[108:111], 0
	v_mfma_f32_16x16x32_bf16 v[4:7], v[76:79], v[112:115], 0
	v_mfma_f32_16x16x32_bf16 v[8:11], v[80:83], v[108:111], 0
	v_mfma_f32_16x16x32_bf16 v[12:15], v[80:83], v[112:115], 0
	v_mfma_f32_16x16x32_bf16 v[16:19], v[84:87], v[108:111], 0
	v_mfma_f32_16x16x32_bf16 v[20:23], v[84:87], v[112:115], 0
	v_mfma_f32_16x16x32_bf16 v[24:27], v[88:91], v[108:111], 0
	v_mfma_f32_16x16x32_bf16 v[28:31], v[88:91], v[112:115], 0
	v_mfma_f32_16x16x32_bf16 v[32:35], v[92:95], v[108:111], 0
	v_mfma_f32_16x16x32_bf16 v[36:39], v[92:95], v[112:115], 0
	v_mfma_f32_16x16x32_bf16 v[40:43], v[96:99], v[108:111], 0
	v_mfma_f32_16x16x32_bf16 v[44:47], v[96:99], v[112:115], 0
	v_mfma_f32_16x16x32_bf16 v[48:51], v[100:103], v[108:111], 0
	v_mfma_f32_16x16x32_bf16 v[52:55], v[100:103], v[112:115], 0
	v_mfma_f32_16x16x32_bf16 v[56:59], v[104:107], v[108:111], 0
	v_mfma_f32_16x16x32_bf16 v[60:63], v[104:107], v[112:115], 0
	v_mfma_f32_16x16x32_bf16 v[0:3], v[116:119], v[148:151], v[0:3]
	v_mfma_f32_16x16x32_bf16 v[4:7], v[116:119], v[152:155], v[4:7]
	v_mfma_f32_16x16x32_bf16 v[8:11], v[120:123], v[148:151], v[8:11]
	v_mfma_f32_16x16x32_bf16 v[12:15], v[120:123], v[152:155], v[12:15]
	v_mfma_f32_16x16x32_bf16 v[16:19], v[124:127], v[148:151], v[16:19]
	v_mfma_f32_16x16x32_bf16 v[20:23], v[124:127], v[152:155], v[20:23]
	v_mfma_f32_16x16x32_bf16 v[24:27], v[128:131], v[148:151], v[24:27]
	v_mfma_f32_16x16x32_bf16 v[28:31], v[128:131], v[152:155], v[28:31]
	v_mfma_f32_16x16x32_bf16 v[32:35], v[132:135], v[148:151], v[32:35]
	v_mfma_f32_16x16x32_bf16 v[36:39], v[132:135], v[152:155], v[36:39]
	v_mfma_f32_16x16x32_bf16 v[40:43], v[136:139], v[148:151], v[40:43]
	v_mfma_f32_16x16x32_bf16 v[44:47], v[136:139], v[152:155], v[44:47]
	v_mfma_f32_16x16x32_bf16 v[48:51], v[140:143], v[148:151], v[48:51]
	v_mfma_f32_16x16x32_bf16 v[52:55], v[140:143], v[152:155], v[52:55]
	v_mfma_f32_16x16x32_bf16 v[56:59], v[144:147], v[148:151], v[56:59]
	v_mfma_f32_16x16x32_bf16 v[60:63], v[144:147], v[152:155], v[60:63]
	global_load_dwordx4 v[108:111], v64, s[34:35] offset:256 nt
	global_load_dwordx4 v[148:151], v64, s[34:35] offset:320 nt
	global_load_dwordx4 v[112:115], v64, s[36:37] offset:256 nt
	global_load_dwordx4 v[152:155], v64, s[36:37] offset:320 nt
	global_load_dwordx4 v[76:79], v64, s[8:9] offset:256 nt
	global_load_dwordx4 v[116:119], v64, s[8:9] offset:320 nt
	global_load_dwordx4 v[80:83], v64, s[10:11] offset:256 nt
	global_load_dwordx4 v[120:123], v64, s[10:11] offset:320 nt
	global_load_dwordx4 v[84:87], v64, s[12:13] offset:256 nt
	global_load_dwordx4 v[124:127], v64, s[12:13] offset:320 nt
	global_load_dwordx4 v[88:91], v64, s[14:15] offset:256 nt
	global_load_dwordx4 v[128:131], v64, s[14:15] offset:320 nt
	global_load_dwordx4 v[92:95], v64, s[24:25] offset:256 nt
	global_load_dwordx4 v[132:135], v64, s[24:25] offset:320 nt
	global_load_dwordx4 v[96:99], v64, s[26:27] offset:256 nt
	global_load_dwordx4 v[136:139], v64, s[26:27] offset:320 nt
	global_load_dwordx4 v[100:103], v64, s[28:29] offset:256 nt
	global_load_dwordx4 v[140:143], v64, s[28:29] offset:320 nt
	global_load_dwordx4 v[104:107], v64, s[30:31] offset:256 nt
	global_load_dwordx4 v[144:147], v64, s[30:31] offset:320 nt
	s_waitcnt vmcnt(20)
; #define SK_LOAD(buf, c) do { _Pragma("unroll") for (int nt = 0; nt < 2; ++nt) fb[buf][nt] = *(const bf16x8*)(pb + nt * rs + 32 * (c)); \
;         _Pragma("unroll") for (int mt = 0; mt < NMT; ++mt) fa[buf][mt] = *(const bf16x8*)(pa + mt * rs + 32 * (c)); } while (0)
; #define SK_MMA(buf) do { _Pragma("unroll") for (int mt = 0; mt < NMT; ++mt) _Pragma("unroll") for (int nt = 0; nt < 2; ++nt) \
;         acc[mt][nt] = __builtin_amdgcn_mfma_f32_16x16x32_bf16(fa[buf][mt], fb[buf][nt], acc[mt][nt], 0, 0, 0); } while (0)
; template <int MT, class Epi>
; DI void skinny_unit(LAS unsigned char* lds, const bf16_t* A, const bf16_t* Wt, int K, int cgi, int k0, int row0, const Epi& E, int tid) {
;     ...
;     SK_LOAD(0, 0); SK_LOAD(1, 1);
;     SK_LOAD(2, 2); SK_MMA(0);
;     SK_LOAD(0, 3); SK_MMA(1);
;     SK_LOAD(1, 4); SK_MMA(2);
;     SK_LOAD(2, 5); SK_MMA(0);
;     SK_LOAD(0, 6); SK_MMA(1);
;     SK_LOAD(1, 7); SK_MMA(2);
;     SK_MMA(0); SK_MMA(1);
	v_mfma_f32_16x16x32_bf16 v[0:3], v[156:159], v[188:191], v[0:3]
	v_mfma_f32_16x16x32_bf16 v[4:7], v[156:159], v[192:195], v[4:7]
	v_mfma_f32_16x16x32_bf16 v[8:11], v[160:163], v[188:191], v[8:11]
	v_mfma_f32_16x16x32_bf16 v[12:15], v[160:163], v[192:195], v[12:15]
	v_mfma_f32_16x16x32_bf16 v[16:19], v[164:167], v[188:191], v[16:19]
	v_mfma_f32_16x16x32_bf16 v[20:23], v[164:167], v[192:195], v[20:23]
	v_mfma_f32_16x16x32_bf16 v[24:27], v[168:171], v[188:191], v[24:27]
	v_mfma_f32_16x16x32_bf16 v[28:31], v[168:171], v[192:195], v[28:31]
	v_mfma_f32_16x16x32_bf16 v[32:35], v[172:175], v[188:191], v[32:35]
	v_mfma_f32_16x16x32_bf16 v[36:39], v[172:175], v[192:195], v[36:39]
	v_mfma_f32_16x16x32_bf16 v[40:43], v[176:179], v[188:191], v[40:43]
	v_mfma_f32_16x16x32_bf16 v[44:47], v[176:179], v[192:195], v[44:47]
	v_mfma_f32_16x16x32_bf16 v[48:51], v[180:183], v[188:191], v[48:51]
	v_mfma_f32_16x16x32_bf16 v[52:55], v[180:183], v[192:195], v[52:55]
	v_mfma_f32_16x16x32_bf16 v[56:59], v[184:187], v[188:191], v[56:59]
	v_mfma_f32_16x16x32_bf16 v[60:63], v[184:187], v[192:195], v[60:63]
	v_mfma_f32_16x16x32_bf16 v[0:3], v[196:199], v[228:231], v[0:3]
	v_mfma_f32_16x16x32_bf16 v[4:7], v[196:199], v[232:235], v[4:7]
	v_mfma_f32_16x16x32_bf16 v[8:11], v[200:203], v[228:231], v[8:11]
	v_mfma_f32_16x16x32_bf16 v[12:15], v[200:203], v[232:235], v[12:15]
	v_mfma_f32_16x16x32_bf16 v[16:19], v[204:207], v[228:231], v[16:19]
	v_mfma_f32_16x16x32_bf16 v[20:23], v[204:207], v[232:235], v[20:23]
	v_mfma_f32_16x16x32_bf16 v[24:27], v[208:211], v[228:231], v[24:27]
	v_mfma_f32_16x16x32_bf16 v[28:31], v[208:211], v[232:235], v[28:31]
	v_mfma_f32_16x16x32_bf16 v[32:35], v[212:215], v[228:231], v[32:35]
	v_mfma_f32_16x16x32_bf16 v[36:39], v[212:215], v[232:235], v[36:39]
	v_mfma_f32_16x16x32_bf16 v[40:43], v[216:219], v[228:231], v[40:43]
	v_mfma_f32_16x16x32_bf16 v[44:47], v[216:219], v[232:235], v[44:47]
	v_mfma_f32_16x16x32_bf16 v[48:51], v[220:223], v[228:231], v[48:51]
	v_mfma_f32_16x16x32_bf16 v[52:55], v[220:223], v[232:235], v[52:55]
	v_mfma_f32_16x16x32_bf16 v[56:59], v[224:227], v[228:231], v[56:59]
	v_mfma_f32_16x16x32_bf16 v[60:63], v[224:227], v[232:235], v[60:63]
	global_load_dwordx4 v[188:191], v64, s[34:35] offset:384 nt
	global_load_dwordx4 v[228:231], v64, s[34:35] offset:448 nt
	global_load_dwordx4 v[192:195], v64, s[36:37] offset:384 nt
	global_load_dwordx4 v[232:235], v64, s[36:37] offset:448 nt
	global_load_dwordx4 v[156:159], v64, s[8:9] offset:384 nt
	global_load_dwordx4 v[196:199], v64, s[8:9] offset:448 nt
	global_load_dwordx4 v[160:163], v64, s[10:11] offset:384 nt
	global_load_dwordx4 v[200:203], v64, s[10:11] offset:448 nt
	global_load_dwordx4 v[164:167], v64, s[12:13] offset:384 nt
	global_load_dwordx4 v[204:207], v64, s[12:13] offset:448 nt
	global_load_dwordx4 v[168:171], v64, s[14:15] offset:384 nt
	global_load_dwordx4 v[208:211], v64, s[14:15] offset:448 nt
	global_load_dwordx4 v[172:175], v64, s[24:25] offset:384 nt
	global_load_dwordx4 v[212:215], v64, s[24:25] offset:448 nt
	global_load_dwordx4 v[176:179], v64, s[26:27] offset:384 nt
	global_load_dwordx4 v[216:219], v64, s[26:27] offset:448 nt
	global_load_dwordx4 v[180:183], v64, s[28:29] offset:384 nt
	global_load_dwordx4 v[220:223], v64, s[28:29] offset:448 nt
	global_load_dwordx4 v[184:187], v64, s[30:31] offset:384 nt
	global_load_dwordx4 v[224:227], v64, s[30:31] offset:448 nt
	s_waitcnt vmcnt(20)
	v_mfma_f32_16x16x32_bf16 v[0:3], v[76:79], v[108:111], v[0:3]
	v_mfma_f32_16x16x32_bf16 v[4:7], v[76:79], v[112:115], v[4:7]
	v_mfma_f32_16x16x32_bf16 v[8:11], v[80:83], v[108:111], v[8:11]
	v_mfma_f32_16x16x32_bf16 v[12:15], v[80:83], v[112:115], v[12:15]
	v_mfma_f32_16x16x32_bf16 v[16:19], v[84:87], v[108:111], v[16:19]
	v_mfma_f32_16x16x32_bf16 v[20:23], v[84:87], v[112:115], v[20:23]
	v_mfma_f32_16x16x32_bf16 v[24:27], v[88:91], v[108:111], v[24:27]
	v_mfma_f32_16x16x32_bf16 v[28:31], v[88:91], v[112:115], v[28:31]
	v_mfma_f32_16x16x32_bf16 v[32:35], v[92:95], v[108:111], v[32:35]
	v_mfma_f32_16x16x32_bf16 v[36:39], v[92:95], v[112:115], v[36:39]
	v_mfma_f32_16x16x32_bf16 v[40:43], v[96:99], v[108:111], v[40:43]
	v_mfma_f32_16x16x32_bf16 v[44:47], v[96:99], v[112:115], v[44:47]
	v_mfma_f32_16x16x32_bf16 v[48:51], v[100:103], v[108:111], v[48:51]
	v_mfma_f32_16x16x32_bf16 v[52:55], v[100:103], v[112:115], v[52:55]
	v_mfma_f32_16x16x32_bf16 v[56:59], v[104:107], v[108:111], v[56:59]
	v_mfma_f32_16x16x32_bf16 v[60:63], v[104:107], v[112:115], v[60:63]
	v_mfma_f32_16x16x32_bf16 v[0:3], v[116:119], v[148:151], v[0:3]
	v_mfma_f32_16x16x32_bf16 v[4:7], v[116:119], v[152:155], v[4:7]
	v_mfma_f32_16x16x32_bf16 v[8:11], v[120:123], v[148:151], v[8:11]
	v_mfma_f32_16x16x32_bf16 v[12:15], v[120:123], v[152:155], v[12:15]
	v_mfma_f32_16x16x32_bf16 v[16:19], v[124:127], v[148:151], v[16:19]
	v_mfma_f32_16x16x32_bf16 v[20:23], v[124:127], v[152:155], v[20:23]
	v_mfma_f32_16x16x32_bf16 v[24:27], v[128:131], v[148:151], v[24:27]
	v_mfma_f32_16x16x32_bf16 v[28:31], v[128:131], v[152:155], v[28:31]
	v_mfma_f32_16x16x32_bf16 v[32:35], v[132:135], v[148:151], v[32:35]
	v_mfma_f32_16x16x32_bf16 v[36:39], v[132:135], v[152:155], v[36:39]
	v_mfma_f32_16x16x32_bf16 v[40:43], v[136:139], v[148:151], v[40:43]
	v_mfma_f32_16x16x32_bf16 v[44:47], v[136:139], v[152:155], v[44:47]
	v_mfma_f32_16x16x32_bf16 v[48:51], v[140:143], v[148:151], v[48:51]
	v_mfma_f32_16x16x32_bf16 v[52:55], v[140:143], v[152:155], v[52:55]
	v_mfma_f32_16x16x32_bf16 v[56:59], v[144:147], v[148:151], v[56:59]
	v_mfma_f32_16x16x32_bf16 v[60:63], v[144:147], v[152:155], v[60:63]
	s_waitcnt vmcnt(0)
; #define LAS __attribute__((address_space(3)))
; #define SK_MMA(buf) do { _Pragma("unroll") for (int mt = 0; mt < NMT; ++mt) _Pragma("unroll") for (int nt = 0; nt < 2; ++nt) \
;         acc[mt][nt] = __builtin_amdgcn_mfma_f32_16x16x32_bf16(fa[buf][mt], fb[buf][nt], acc[mt][nt], 0, 0, 0); } while (0)
; template <int MT, class Epi>
; DI void skinny_unit(LAS unsigned char* lds, const bf16_t* A, const bf16_t* Wt, int K, int cgi, int k0, int row0, const Epi& E, int tid) {
;     ...
;     SK_MMA(0); SK_MMA(1);
;     ...
;     constexpr int NR = 32 * MT;
;     LAS float* red = (LAS float*)lds;
; #pragma unroll
;     for (int mt = 0; mt < NMT; ++mt)
; #pragma unroll
;         for (int nt = 0; nt < 2; ++nt)
; #pragma unroll
;             for (int j = 0; j < 4; ++j) red[(wid * NR + mt * 16 + 4 * fq + j) * 32 + nt * 16 + fr] = acc[mt][nt][j];
;     __syncthreads();
;     if (MT == 4) {
;         const int row = tid >> 2, c8 = (tid & 3) * 8;
;         f32x4 sa = {0.f, 0.f, 0.f, 0.f}, sb = {0.f, 0.f, 0.f, 0.f};
; #pragma unroll
;         for (int w = 0; w < 8; ++w) { sa += *(const LAS f32x4*)(red + (w * NR + row) * 32 + c8); sb += *(const LAS f32x4*)(red + (w * NR + row) * 32 + c8 + 4); }
;         E(row0 + row, c0 + c8, sa); E(row0 + row, c0 + c8 + 4, sb);
;     } else if (tid < 8 * NR) {
;         const int row = tid >> 3, c4 = (tid & 7) * 4;
;         f32x4 sa = {0.f, 0.f, 0.f, 0.f};
; #pragma unroll
;         for (int w = 0; w < 8; ++w) sa += *(const LAS f32x4*)(red + (w * NR + row) * 32 + c4);
;         E(row0 + row, c0 + c4, sa);
;     }
;     __syncthreads();
; }
	v_mfma_f32_16x16x32_bf16 v[0:3], v[156:159], v[188:191], v[0:3]
	v_mfma_f32_16x16x32_bf16 v[4:7], v[156:159], v[192:195], v[4:7]
	v_mfma_f32_16x16x32_bf16 v[8:11], v[160:163], v[188:191], v[8:11]
	v_mfma_f32_16x16x32_bf16 v[12:15], v[160:163], v[192:195], v[12:15]
	v_mfma_f32_16x16x32_bf16 v[16:19], v[164:167], v[188:191], v[16:19]
	v_mfma_f32_16x16x32_bf16 v[20:23], v[164:167], v[192:195], v[20:23]
	v_mfma_f32_16x16x32_bf16 v[24:27], v[168:171], v[188:191], v[24:27]
	v_mfma_f32_16x16x32_bf16 v[28:31], v[168:171], v[192:195], v[28:31]
	v_mfma_f32_16x16x32_bf16 v[32:35], v[172:175], v[188:191], v[32:35]
	v_mfma_f32_16x16x32_bf16 v[36:39], v[172:175], v[192:195], v[36:39]
	v_mfma_f32_16x16x32_bf16 v[40:43], v[176:179], v[188:191], v[40:43]
	v_mfma_f32_16x16x32_bf16 v[44:47], v[176:179], v[192:195], v[44:47]
	v_mfma_f32_16x16x32_bf16 v[48:51], v[180:183], v[188:191], v[48:51]
	v_mfma_f32_16x16x32_bf16 v[52:55], v[180:183], v[192:195], v[52:55]
	v_mfma_f32_16x16x32_bf16 v[56:59], v[184:187], v[188:191], v[56:59]
	v_mfma_f32_16x16x32_bf16 v[60:63], v[184:187], v[192:195], v[60:63]
	v_mfma_f32_16x16x32_bf16 v[0:3], v[196:199], v[228:231], v[0:3]
	v_mfma_f32_16x16x32_bf16 v[4:7], v[196:199], v[232:235], v[4:7]
	v_mfma_f32_16x16x32_bf16 v[8:11], v[200:203], v[228:231], v[8:11]
	v_mfma_f32_16x16x32_bf16 v[12:15], v[200:203], v[232:235], v[12:15]
	v_mfma_f32_16x16x32_bf16 v[16:19], v[204:207], v[228:231], v[16:19]
	v_mfma_f32_16x16x32_bf16 v[20:23], v[204:207], v[232:235], v[20:23]
	v_mfma_f32_16x16x32_bf16 v[24:27], v[208:211], v[228:231], v[24:27]
	v_mfma_f32_16x16x32_bf16 v[28:31], v[208:211], v[232:235], v[28:31]
	v_mfma_f32_16x16x32_bf16 v[32:35], v[212:215], v[228:231], v[32:35]
	v_mfma_f32_16x16x32_bf16 v[36:39], v[212:215], v[232:235], v[36:39]
	v_mfma_f32_16x16x32_bf16 v[40:43], v[216:219], v[228:231], v[40:43]
	v_mfma_f32_16x16x32_bf16 v[44:47], v[216:219], v[232:235], v[44:47]
	v_mfma_f32_16x16x32_bf16 v[48:51], v[220:223], v[228:231], v[48:51]
	v_mfma_f32_16x16x32_bf16 v[52:55], v[220:223], v[232:235], v[52:55]
	v_mfma_f32_16x16x32_bf16 v[56:59], v[224:227], v[228:231], v[56:59]
	v_mfma_f32_16x16x32_bf16 v[60:63], v[224:227], v[232:235], v[60:63]
	v_add_u32_e32 v77, 0x800, v65
	v_add_u32_e32 v78, 0x1000, v65
	v_add_u32_e32 v79, 0x1800, v65
	v_add_u32_e32 v80, 0x2000, v65
	v_add_u32_e32 v81, 0x2800, v65
	v_add_u32_e32 v82, 0x3000, v65
	v_add_u32_e32 v83, 0x3800, v65
	s_nop 7
	s_nop 3
	ds_write2_b32 v65, v0, v4 offset1:16
	ds_write2_b32 v65, v1, v5 offset0:32 offset1:48
	ds_write2_b32 v65, v2, v6 offset0:64 offset1:80
	ds_write2_b32 v65, v3, v7 offset0:96 offset1:112
	ds_write2_b32 v77, v8, v12 offset1:16
	ds_write2_b32 v77, v9, v13 offset0:32 offset1:48
	ds_write2_b32 v77, v10, v14 offset0:64 offset1:80
	ds_write2_b32 v77, v11, v15 offset0:96 offset1:112
	ds_write2_b32 v78, v16, v20 offset1:16
	ds_write2_b32 v78, v17, v21 offset0:32 offset1:48
	ds_write2_b32 v78, v18, v22 offset0:64 offset1:80
	ds_write2_b32 v78, v19, v23 offset0:96 offset1:112
	ds_write2_b32 v79, v24, v28 offset1:16
	ds_write2_b32 v79, v25, v29 offset0:32 offset1:48
	ds_write2_b32 v79, v26, v30 offset0:64 offset1:80
	ds_write2_b32 v79, v27, v31 offset0:96 offset1:112
	ds_write2_b32 v80, v32, v36 offset1:16
	ds_write2_b32 v80, v33, v37 offset0:32 offset1:48
	ds_write2_b32 v80, v34, v38 offset0:64 offset1:80
	ds_write2_b32 v80, v35, v39 offset0:96 offset1:112
	ds_write2_b32 v81, v40, v44 offset1:16
	ds_write2_b32 v81, v41, v45 offset0:32 offset1:48
	ds_write2_b32 v81, v42, v46 offset0:64 offset1:80
	ds_write2_b32 v81, v43, v47 offset0:96 offset1:112
	ds_write2_b32 v82, v48, v52 offset1:16
	ds_write2_b32 v82, v49, v53 offset0:32 offset1:48
	ds_write2_b32 v82, v50, v54 offset0:64 offset1:80
	ds_write2_b32 v82, v51, v55 offset0:96 offset1:112
	ds_write2_b32 v83, v56, v60 offset1:16
	ds_write2_b32 v83, v57, v61 offset0:32 offset1:48
	ds_write2_b32 v83, v58, v62 offset0:64 offset1:80
	ds_write2_b32 v83, v59, v63 offset0:96 offset1:112
	s_waitcnt lgkmcnt(0)
	s_barrier
	ds_read_b128 v[76:79], v66 offset:0
	ds_read_b128 v[80:83], v66 offset:16
	ds_read_b128 v[84:87], v66 offset:16384
	ds_read_b128 v[88:91], v66 offset:16400
	ds_read_b128 v[92:95], v66 offset:32768
	ds_read_b128 v[96:99], v66 offset:32784
	ds_read_b128 v[100:103], v66 offset:49152
	ds_read_b128 v[104:107], v66 offset:49168
	ds_read_b128 v[108:111], v67 offset:0
	ds_read_b128 v[112:115], v67 offset:16
	ds_read_b128 v[116:119], v67 offset:16384
	ds_read_b128 v[120:123], v67 offset:16400
	ds_read_b128 v[124:127], v67 offset:32768
	ds_read_b128 v[128:131], v67 offset:32784
	ds_read_b128 v[132:135], v67 offset:49152
	ds_read_b128 v[136:139], v67 offset:49168
	s_waitcnt lgkmcnt(12)
	v_pk_add_f32 v[76:77], v[76:77], v[84:85]
	v_pk_add_f32 v[78:79], v[78:79], v[86:87]
	v_pk_add_f32 v[80:81], v[80:81], v[88:89]
	v_pk_add_f32 v[82:83], v[82:83], v[90:91]
	s_waitcnt lgkmcnt(10)
	v_pk_add_f32 v[76:77], v[76:77], v[92:93]
	v_pk_add_f32 v[78:79], v[78:79], v[94:95]
	v_pk_add_f32 v[80:81], v[80:81], v[96:97]
	v_pk_add_f32 v[82:83], v[82:83], v[98:99]
	s_waitcnt lgkmcnt(8)
	v_pk_add_f32 v[76:77], v[76:77], v[100:101]
	v_pk_add_f32 v[78:79], v[78:79], v[102:103]
	v_pk_add_f32 v[80:81], v[80:81], v[104:105]
	v_pk_add_f32 v[82:83], v[82:83], v[106:107]
	s_waitcnt lgkmcnt(6)
	v_pk_add_f32 v[76:77], v[76:77], v[108:109]
	v_pk_add_f32 v[78:79], v[78:79], v[110:111]
	v_pk_add_f32 v[80:81], v[80:81], v[112:113]
	v_pk_add_f32 v[82:83], v[82:83], v[114:115]
	s_waitcnt lgkmcnt(4)
	v_pk_add_f32 v[76:77], v[76:77], v[116:117]
	v_pk_add_f32 v[78:79], v[78:79], v[118:119]
	v_pk_add_f32 v[80:81], v[80:81], v[120:121]
	v_pk_add_f32 v[82:83], v[82:83], v[122:123]
	s_waitcnt lgkmcnt(2)
	v_pk_add_f32 v[76:77], v[76:77], v[124:125]
	v_pk_add_f32 v[78:79], v[78:79], v[126:127]
	v_pk_add_f32 v[80:81], v[80:81], v[128:129]
	v_pk_add_f32 v[82:83], v[82:83], v[130:131]
	s_waitcnt lgkmcnt(0)
	v_pk_add_f32 v[76:77], v[76:77], v[132:133]
	v_pk_add_f32 v[78:79], v[78:79], v[134:135]
	v_pk_add_f32 v[80:81], v[80:81], v[136:137]
	v_pk_add_f32 v[82:83], v[82:83], v[138:139]
	v_max_f32_e32 v76, 0, v76
	v_max_f32_e32 v77, 0, v77
	v_max_f32_e32 v78, 0, v78
	v_max_f32_e32 v79, 0, v79
	v_max_f32_e32 v80, 0, v80
	v_max_f32_e32 v81, 0, v81
	v_max_f32_e32 v82, 0, v82
	v_max_f32_e32 v83, 0, v83
	v_pk_mul_f32 v[76:77], v[76:77], v[76:77]
	v_pk_mul_f32 v[78:79], v[78:79], v[78:79]
	v_pk_mul_f32 v[80:81], v[80:81], v[80:81]
	v_pk_mul_f32 v[82:83], v[82:83], v[82:83]
	v_cvt_pk_bf16_f32 v84, v76, v77
	v_cvt_pk_bf16_f32 v85, v78, v79
	v_cvt_pk_bf16_f32 v86, v80, v81
	v_cvt_pk_bf16_f32 v87, v82, v83
	global_store_dwordx4 v68, v[84:87], s[38:39]
	s_add_i32 s0, s0, s64
	s_cmpk_lt_i32 s0, 0x100
	s_barrier
	s_cbranch_scc1 .Lsk6_loop
